# SB attention epilogue: gate pieces prefetched together, straight-lined, Y stores write-through
# speedup vs baseline: 1.0333x; 1.0012x over previous
.LBB0_557:
	v_ashrrev_i32_e32 v128, 4, v147
	v_ashrrev_i32_e32 v129, 31, v128
	v_lshlrev_b64 v[132:133], 13, v[128:129]
	v_lshl_add_u64 v[132:133], v[144:145], 0, v[132:133]
	s_mov_b32 s4, 0x40000
	s_mov_b32 s5, 0
	v_mad_u32_u24 v130, v128, s11, v146
	global_load_dwordx4 v[96:99], v[132:133], off offset:3072
	v_lshl_add_u64 v[132:133], v[132:133], 0, s[4:5]
	global_load_dwordx4 v[100:103], v[132:133], off offset:3072
	v_lshl_add_u64 v[132:133], v[132:133], 0, s[4:5]
	global_load_dwordx4 v[104:107], v[132:133], off offset:3072
	v_lshl_add_u64 v[132:133], v[132:133], 0, s[4:5]
	global_load_dwordx4 v[108:111], v[132:133], off offset:3072
	v_lshl_add_u64 v[132:133], v[132:133], 0, s[4:5]
	global_load_dwordx4 v[112:115], v[132:133], off offset:3072
	v_lshl_add_u64 v[132:133], v[132:133], 0, s[4:5]
	global_load_dwordx4 v[116:119], v[132:133], off offset:3072
	v_lshl_add_u64 v[132:133], v[132:133], 0, s[4:5]
	global_load_dwordx4 v[120:123], v[132:133], off offset:3072
	v_lshl_add_u64 v[132:133], v[132:133], 0, s[4:5]
	global_load_dwordx4 v[124:127], v[132:133], off offset:3072
	v_cvt_pk_bf16_f32 v2, v16, v17
	v_cvt_pk_bf16_f32 v3, v18, v19
	v_lshl_add_u32 v1, v149, 3, v151
	v_cvt_pk_bf16_f32 v4, v20, v21
	v_cvt_pk_bf16_f32 v5, v22, v23
	s_waitcnt lgkmcnt(0)
	s_barrier
	ds_write2_b64 v1, v[2:3], v[4:5] offset1:2
	v_cvt_pk_bf16_f32 v2, v24, v25
	v_cvt_pk_bf16_f32 v3, v26, v27
	v_cvt_pk_bf16_f32 v4, v28, v29
	v_cvt_pk_bf16_f32 v5, v30, v31
	ds_write2_b64 v1, v[2:3], v[4:5] offset0:4 offset1:6
	v_cvt_pk_bf16_f32 v2, v32, v33
	v_cvt_pk_bf16_f32 v3, v34, v35
	v_cvt_pk_bf16_f32 v4, v36, v37
	v_cvt_pk_bf16_f32 v5, v38, v39
	ds_write2_b64 v1, v[2:3], v[4:5] offset0:8 offset1:10
	v_cvt_pk_bf16_f32 v2, v40, v41
	v_cvt_pk_bf16_f32 v3, v42, v43
	v_cvt_pk_bf16_f32 v4, v44, v45
	v_cvt_pk_bf16_f32 v5, v46, v47
	s_lshl_b64 s[0:1], s[6:7], 20
	ds_write2_b64 v1, v[2:3], v[4:5] offset0:12 offset1:14
	v_cvt_pk_bf16_f32 v2, v48, v49
	v_cvt_pk_bf16_f32 v3, v50, v51
	v_cvt_pk_bf16_f32 v4, v52, v53
	v_cvt_pk_bf16_f32 v5, v54, v55
	s_add_u32 s0, s18, s0
	ds_write2_b64 v1, v[2:3], v[4:5] offset0:16 offset1:18
	v_cvt_pk_bf16_f32 v2, v56, v57
	v_cvt_pk_bf16_f32 v3, v58, v59
	v_cvt_pk_bf16_f32 v4, v60, v61
	v_cvt_pk_bf16_f32 v5, v62, v63
	s_addc_u32 s1, s19, s1
	ds_write2_b64 v1, v[2:3], v[4:5] offset0:20 offset1:22
	v_cvt_pk_bf16_f32 v2, v64, v65
	v_cvt_pk_bf16_f32 v3, v66, v67
	v_cvt_pk_bf16_f32 v4, v68, v69
	v_cvt_pk_bf16_f32 v5, v70, v71
	s_add_u32 s0, s0, s9
	ds_write2_b64 v1, v[2:3], v[4:5] offset0:24 offset1:26
	v_cvt_pk_bf16_f32 v2, v72, v73
	v_cvt_pk_bf16_f32 v3, v74, v75
	v_cvt_pk_bf16_f32 v4, v76, v77
	v_cvt_pk_bf16_f32 v5, v78, v79
	s_addc_u32 s1, s1, 0
	ds_write2_b64 v1, v[2:3], v[4:5] offset0:28 offset1:30
	v_lshlrev_b32_e32 v2, 1, v148
	v_mov_b32_e32 v3, v0
	v_lshl_add_u64 v[2:3], s[0:1], 0, v[2:3]
	s_mov_b32 s0, 0
	s_waitcnt lgkmcnt(0)
	s_barrier
.LBB0_558:
	ds_read_b128 v[4:7], v130
	s_waitcnt vmcnt(7)
	v_mov_b32_e32 v8, v96
	v_mov_b32_e32 v9, v97
	v_mov_b32_e32 v10, v98
	v_mov_b32_e32 v11, v99
	s_waitcnt lgkmcnt(0)
	v_lshlrev_b32_e32 v18, 16, v4
	v_and_b32_e32 v19, 0xffff0000, v4
	v_lshlrev_b32_e32 v14, 16, v8
	v_and_b32_e32 v15, 0xffff0000, v8
	v_mul_f32_e32 v8, 0xbfb8aa3b, v14
	v_mul_f32_e32 v4, 0xbfb8aa3b, v15
	v_exp_f32_e32 v8, v8
	v_exp_f32_e32 v4, v4
	v_add_f32_e32 v8, 1.0, v8
	v_add_f32_e32 v4, 1.0, v4
	v_rcp_f32_e32 v16, v8
	v_rcp_f32_e32 v17, v4
	v_lshlrev_b32_e32 v8, 16, v9
	v_and_b32_e32 v9, 0xffff0000, v9
	v_pk_mul_f32 v[14:15], v[16:17], v[14:15]
	s_nop 0
	v_pk_mul_f32 v[14:15], v[14:15], v[18:19]
	v_lshlrev_b32_e32 v16, 16, v5
	v_cvt_pk_bf16_f32 v4, v14, v15
	v_mul_f32_e32 v14, 0xbfb8aa3b, v8
	v_and_b32_e32 v17, 0xffff0000, v5
	v_mul_f32_e32 v5, 0xbfb8aa3b, v9
	v_exp_f32_e32 v14, v14
	v_exp_f32_e32 v5, v5
	v_add_f32_e32 v14, 1.0, v14
	v_add_f32_e32 v5, 1.0, v5
	v_rcp_f32_e32 v14, v14
	v_rcp_f32_e32 v15, v5
	s_nop 0
	v_pk_mul_f32 v[8:9], v[14:15], v[8:9]
	s_nop 0
	v_pk_mul_f32 v[8:9], v[8:9], v[16:17]
	v_lshlrev_b32_e32 v16, 16, v6
	v_cvt_pk_bf16_f32 v5, v8, v9
	v_lshlrev_b32_e32 v8, 16, v10
	v_and_b32_e32 v9, 0xffff0000, v10
	v_mul_f32_e32 v10, 0xbfb8aa3b, v8
	v_and_b32_e32 v17, 0xffff0000, v6
	v_mul_f32_e32 v6, 0xbfb8aa3b, v9
	v_exp_f32_e32 v10, v10
	v_exp_f32_e32 v6, v6
	v_add_f32_e32 v10, 1.0, v10
	v_add_f32_e32 v6, 1.0, v6
	v_rcp_f32_e32 v14, v10
	v_rcp_f32_e32 v15, v6
	s_nop 0
	v_pk_mul_f32 v[8:9], v[14:15], v[8:9]
	s_nop 0
	v_pk_mul_f32 v[8:9], v[8:9], v[16:17]
	v_lshlrev_b32_e32 v14, 16, v7
	v_cvt_pk_bf16_f32 v6, v8, v9
	v_lshlrev_b32_e32 v8, 16, v11
	v_and_b32_e32 v9, 0xffff0000, v11
	v_mul_f32_e32 v10, 0xbfb8aa3b, v8
	v_and_b32_e32 v15, 0xffff0000, v7
	v_mul_f32_e32 v7, 0xbfb8aa3b, v9
	v_exp_f32_e32 v10, v10
	v_exp_f32_e32 v7, v7
	v_add_f32_e32 v10, 1.0, v10
	v_add_f32_e32 v7, 1.0, v7
	v_rcp_f32_e32 v10, v10
	v_rcp_f32_e32 v11, v7
	s_nop 0
	v_pk_mul_f32 v[8:9], v[10:11], v[8:9]
	s_nop 0
	v_pk_mul_f32 v[8:9], v[8:9], v[14:15]
	s_nop 0
	v_cvt_pk_bf16_f32 v7, v8, v9
	v_mov_b32_e32 v12, v128
	v_mov_b32_e32 v13, 0
	v_lshlrev_b64 v[8:9], 12, v[12:13]
	v_lshl_add_u64 v[8:9], v[2:3], 0, v[8:9]
	global_store_dwordx4 v[8:9], v[4:7], off sc1
	s_nop 1
	ds_read_b128 v[4:7], v130 offset:8704
	s_waitcnt vmcnt(7)
	v_mov_b32_e32 v8, v100
	v_mov_b32_e32 v9, v101
	v_mov_b32_e32 v10, v102
	v_mov_b32_e32 v11, v103
	s_waitcnt lgkmcnt(0)
	v_lshlrev_b32_e32 v18, 16, v4
	v_and_b32_e32 v19, 0xffff0000, v4
	v_lshlrev_b32_e32 v14, 16, v8
	v_and_b32_e32 v15, 0xffff0000, v8
	v_mul_f32_e32 v8, 0xbfb8aa3b, v14
	v_mul_f32_e32 v4, 0xbfb8aa3b, v15
	v_exp_f32_e32 v8, v8
	v_exp_f32_e32 v4, v4
	v_add_f32_e32 v8, 1.0, v8
	v_add_f32_e32 v4, 1.0, v4
	v_rcp_f32_e32 v16, v8
	v_rcp_f32_e32 v17, v4
	v_lshlrev_b32_e32 v8, 16, v9
	v_and_b32_e32 v9, 0xffff0000, v9
	v_pk_mul_f32 v[14:15], v[16:17], v[14:15]
	s_nop 0
	v_pk_mul_f32 v[14:15], v[14:15], v[18:19]
	v_lshlrev_b32_e32 v16, 16, v5
	v_cvt_pk_bf16_f32 v4, v14, v15
	v_mul_f32_e32 v14, 0xbfb8aa3b, v8
	v_and_b32_e32 v17, 0xffff0000, v5
	v_mul_f32_e32 v5, 0xbfb8aa3b, v9
	v_exp_f32_e32 v14, v14
	v_exp_f32_e32 v5, v5
	v_add_f32_e32 v14, 1.0, v14
	v_add_f32_e32 v5, 1.0, v5
	v_rcp_f32_e32 v14, v14
	v_rcp_f32_e32 v15, v5
	s_nop 0
	v_pk_mul_f32 v[8:9], v[14:15], v[8:9]
	s_nop 0
	v_pk_mul_f32 v[8:9], v[8:9], v[16:17]
	v_lshlrev_b32_e32 v16, 16, v6
	v_cvt_pk_bf16_f32 v5, v8, v9
	v_lshlrev_b32_e32 v8, 16, v10
	v_and_b32_e32 v9, 0xffff0000, v10
	v_mul_f32_e32 v10, 0xbfb8aa3b, v8
	v_and_b32_e32 v17, 0xffff0000, v6
	v_mul_f32_e32 v6, 0xbfb8aa3b, v9
	v_exp_f32_e32 v10, v10
	v_exp_f32_e32 v6, v6
	v_add_f32_e32 v10, 1.0, v10
	v_add_f32_e32 v6, 1.0, v6
	v_rcp_f32_e32 v14, v10
	v_rcp_f32_e32 v15, v6
	s_nop 0
	v_pk_mul_f32 v[8:9], v[14:15], v[8:9]
	s_nop 0
	v_pk_mul_f32 v[8:9], v[8:9], v[16:17]
	v_lshlrev_b32_e32 v14, 16, v7
	v_cvt_pk_bf16_f32 v6, v8, v9
	v_lshlrev_b32_e32 v8, 16, v11
	v_and_b32_e32 v9, 0xffff0000, v11
	v_mul_f32_e32 v10, 0xbfb8aa3b, v8
	v_and_b32_e32 v15, 0xffff0000, v7
	v_mul_f32_e32 v7, 0xbfb8aa3b, v9
	v_exp_f32_e32 v10, v10
	v_exp_f32_e32 v7, v7
	v_add_f32_e32 v10, 1.0, v10
	v_add_f32_e32 v7, 1.0, v7
	v_rcp_f32_e32 v10, v10
	v_rcp_f32_e32 v11, v7
	s_nop 0
	v_pk_mul_f32 v[8:9], v[10:11], v[8:9]
	s_nop 0
	v_pk_mul_f32 v[8:9], v[8:9], v[14:15]
	s_nop 0
	v_cvt_pk_bf16_f32 v7, v8, v9
	v_add_u32_e32 v12, 32, v128
	v_mov_b32_e32 v13, 0
	v_lshlrev_b64 v[8:9], 12, v[12:13]
	v_lshl_add_u64 v[8:9], v[2:3], 0, v[8:9]
	global_store_dwordx4 v[8:9], v[4:7], off sc1
	s_nop 1
	ds_read_b128 v[4:7], v130 offset:17408
	s_waitcnt vmcnt(7)
	v_mov_b32_e32 v8, v104
	v_mov_b32_e32 v9, v105
	v_mov_b32_e32 v10, v106
	v_mov_b32_e32 v11, v107
	s_waitcnt lgkmcnt(0)
	v_lshlrev_b32_e32 v18, 16, v4
	v_and_b32_e32 v19, 0xffff0000, v4
	v_lshlrev_b32_e32 v14, 16, v8
	v_and_b32_e32 v15, 0xffff0000, v8
	v_mul_f32_e32 v8, 0xbfb8aa3b, v14
	v_mul_f32_e32 v4, 0xbfb8aa3b, v15
	v_exp_f32_e32 v8, v8
	v_exp_f32_e32 v4, v4
	v_add_f32_e32 v8, 1.0, v8
	v_add_f32_e32 v4, 1.0, v4
	v_rcp_f32_e32 v16, v8
	v_rcp_f32_e32 v17, v4
	v_lshlrev_b32_e32 v8, 16, v9
	v_and_b32_e32 v9, 0xffff0000, v9
	v_pk_mul_f32 v[14:15], v[16:17], v[14:15]
	s_nop 0
	v_pk_mul_f32 v[14:15], v[14:15], v[18:19]
	v_lshlrev_b32_e32 v16, 16, v5
	v_cvt_pk_bf16_f32 v4, v14, v15
	v_mul_f32_e32 v14, 0xbfb8aa3b, v8
	v_and_b32_e32 v17, 0xffff0000, v5
	v_mul_f32_e32 v5, 0xbfb8aa3b, v9
	v_exp_f32_e32 v14, v14
	v_exp_f32_e32 v5, v5
	v_add_f32_e32 v14, 1.0, v14
	v_add_f32_e32 v5, 1.0, v5
	v_rcp_f32_e32 v14, v14
	v_rcp_f32_e32 v15, v5
	s_nop 0
	v_pk_mul_f32 v[8:9], v[14:15], v[8:9]
	s_nop 0
	v_pk_mul_f32 v[8:9], v[8:9], v[16:17]
	v_lshlrev_b32_e32 v16, 16, v6
	v_cvt_pk_bf16_f32 v5, v8, v9
	v_lshlrev_b32_e32 v8, 16, v10
	v_and_b32_e32 v9, 0xffff0000, v10
	v_mul_f32_e32 v10, 0xbfb8aa3b, v8
	v_and_b32_e32 v17, 0xffff0000, v6
	v_mul_f32_e32 v6, 0xbfb8aa3b, v9
	v_exp_f32_e32 v10, v10
	v_exp_f32_e32 v6, v6
	v_add_f32_e32 v10, 1.0, v10
	v_add_f32_e32 v6, 1.0, v6
	v_rcp_f32_e32 v14, v10
	v_rcp_f32_e32 v15, v6
	s_nop 0
	v_pk_mul_f32 v[8:9], v[14:15], v[8:9]
	s_nop 0
	v_pk_mul_f32 v[8:9], v[8:9], v[16:17]
	v_lshlrev_b32_e32 v14, 16, v7
	v_cvt_pk_bf16_f32 v6, v8, v9
	v_lshlrev_b32_e32 v8, 16, v11
	v_and_b32_e32 v9, 0xffff0000, v11
	v_mul_f32_e32 v10, 0xbfb8aa3b, v8
	v_and_b32_e32 v15, 0xffff0000, v7
	v_mul_f32_e32 v7, 0xbfb8aa3b, v9
	v_exp_f32_e32 v10, v10
	v_exp_f32_e32 v7, v7
	v_add_f32_e32 v10, 1.0, v10
	v_add_f32_e32 v7, 1.0, v7
	v_rcp_f32_e32 v10, v10
	v_rcp_f32_e32 v11, v7
	s_nop 0
	v_pk_mul_f32 v[8:9], v[10:11], v[8:9]
	s_nop 0
	v_pk_mul_f32 v[8:9], v[8:9], v[14:15]
	s_nop 0
	v_cvt_pk_bf16_f32 v7, v8, v9
	v_add_u32_e32 v12, 64, v128
	v_mov_b32_e32 v13, 0
	v_lshlrev_b64 v[8:9], 12, v[12:13]
	v_lshl_add_u64 v[8:9], v[2:3], 0, v[8:9]
	global_store_dwordx4 v[8:9], v[4:7], off sc1
	s_nop 1
	ds_read_b128 v[4:7], v130 offset:26112
	s_waitcnt vmcnt(7)
	v_mov_b32_e32 v8, v108
	v_mov_b32_e32 v9, v109
	v_mov_b32_e32 v10, v110
	v_mov_b32_e32 v11, v111
	s_waitcnt lgkmcnt(0)
	v_lshlrev_b32_e32 v18, 16, v4
	v_and_b32_e32 v19, 0xffff0000, v4
	v_lshlrev_b32_e32 v14, 16, v8
	v_and_b32_e32 v15, 0xffff0000, v8
	v_mul_f32_e32 v8, 0xbfb8aa3b, v14
	v_mul_f32_e32 v4, 0xbfb8aa3b, v15
	v_exp_f32_e32 v8, v8
	v_exp_f32_e32 v4, v4
	v_add_f32_e32 v8, 1.0, v8
	v_add_f32_e32 v4, 1.0, v4
	v_rcp_f32_e32 v16, v8
	v_rcp_f32_e32 v17, v4
	v_lshlrev_b32_e32 v8, 16, v9
	v_and_b32_e32 v9, 0xffff0000, v9
	v_pk_mul_f32 v[14:15], v[16:17], v[14:15]
	s_nop 0
	v_pk_mul_f32 v[14:15], v[14:15], v[18:19]
	v_lshlrev_b32_e32 v16, 16, v5
	v_cvt_pk_bf16_f32 v4, v14, v15
	v_mul_f32_e32 v14, 0xbfb8aa3b, v8
	v_and_b32_e32 v17, 0xffff0000, v5
	v_mul_f32_e32 v5, 0xbfb8aa3b, v9
	v_exp_f32_e32 v14, v14
	v_exp_f32_e32 v5, v5
	v_add_f32_e32 v14, 1.0, v14
	v_add_f32_e32 v5, 1.0, v5
	v_rcp_f32_e32 v14, v14
	v_rcp_f32_e32 v15, v5
	s_nop 0
	v_pk_mul_f32 v[8:9], v[14:15], v[8:9]
	s_nop 0
	v_pk_mul_f32 v[8:9], v[8:9], v[16:17]
	v_lshlrev_b32_e32 v16, 16, v6
	v_cvt_pk_bf16_f32 v5, v8, v9
	v_lshlrev_b32_e32 v8, 16, v10
	v_and_b32_e32 v9, 0xffff0000, v10
	v_mul_f32_e32 v10, 0xbfb8aa3b, v8
	v_and_b32_e32 v17, 0xffff0000, v6
	v_mul_f32_e32 v6, 0xbfb8aa3b, v9
	v_exp_f32_e32 v10, v10
	v_exp_f32_e32 v6, v6
	v_add_f32_e32 v10, 1.0, v10
	v_add_f32_e32 v6, 1.0, v6
	v_rcp_f32_e32 v14, v10
	v_rcp_f32_e32 v15, v6
	s_nop 0
	v_pk_mul_f32 v[8:9], v[14:15], v[8:9]
	s_nop 0
	v_pk_mul_f32 v[8:9], v[8:9], v[16:17]
	v_lshlrev_b32_e32 v14, 16, v7
	v_cvt_pk_bf16_f32 v6, v8, v9
	v_lshlrev_b32_e32 v8, 16, v11
	v_and_b32_e32 v9, 0xffff0000, v11
	v_mul_f32_e32 v10, 0xbfb8aa3b, v8
	v_and_b32_e32 v15, 0xffff0000, v7
	v_mul_f32_e32 v7, 0xbfb8aa3b, v9
	v_exp_f32_e32 v10, v10
	v_exp_f32_e32 v7, v7
	v_add_f32_e32 v10, 1.0, v10
	v_add_f32_e32 v7, 1.0, v7
	v_rcp_f32_e32 v10, v10
	v_rcp_f32_e32 v11, v7
	s_nop 0
	v_pk_mul_f32 v[8:9], v[10:11], v[8:9]
	s_nop 0
	v_pk_mul_f32 v[8:9], v[8:9], v[14:15]
	s_nop 0
	v_cvt_pk_bf16_f32 v7, v8, v9
	v_add_u32_e32 v12, 96, v128
	v_mov_b32_e32 v13, 0
	v_lshlrev_b64 v[8:9], 12, v[12:13]
	v_lshl_add_u64 v[8:9], v[2:3], 0, v[8:9]
	global_store_dwordx4 v[8:9], v[4:7], off sc1
	s_nop 1
	ds_read_b128 v[4:7], v130 offset:34816
	s_waitcnt vmcnt(7)
	v_mov_b32_e32 v8, v112
	v_mov_b32_e32 v9, v113
	v_mov_b32_e32 v10, v114
	v_mov_b32_e32 v11, v115
	s_waitcnt lgkmcnt(0)
	v_lshlrev_b32_e32 v18, 16, v4
	v_and_b32_e32 v19, 0xffff0000, v4
	v_lshlrev_b32_e32 v14, 16, v8
	v_and_b32_e32 v15, 0xffff0000, v8
	v_mul_f32_e32 v8, 0xbfb8aa3b, v14
	v_mul_f32_e32 v4, 0xbfb8aa3b, v15
	v_exp_f32_e32 v8, v8
	v_exp_f32_e32 v4, v4
	v_add_f32_e32 v8, 1.0, v8
	v_add_f32_e32 v4, 1.0, v4
	v_rcp_f32_e32 v16, v8
	v_rcp_f32_e32 v17, v4
	v_lshlrev_b32_e32 v8, 16, v9
	v_and_b32_e32 v9, 0xffff0000, v9
	v_pk_mul_f32 v[14:15], v[16:17], v[14:15]
	s_nop 0
	v_pk_mul_f32 v[14:15], v[14:15], v[18:19]
	v_lshlrev_b32_e32 v16, 16, v5
	v_cvt_pk_bf16_f32 v4, v14, v15
	v_mul_f32_e32 v14, 0xbfb8aa3b, v8
	v_and_b32_e32 v17, 0xffff0000, v5
	v_mul_f32_e32 v5, 0xbfb8aa3b, v9
	v_exp_f32_e32 v14, v14
	v_exp_f32_e32 v5, v5
	v_add_f32_e32 v14, 1.0, v14
	v_add_f32_e32 v5, 1.0, v5
	v_rcp_f32_e32 v14, v14
	v_rcp_f32_e32 v15, v5
	s_nop 0
	v_pk_mul_f32 v[8:9], v[14:15], v[8:9]
	s_nop 0
	v_pk_mul_f32 v[8:9], v[8:9], v[16:17]
	v_lshlrev_b32_e32 v16, 16, v6
	v_cvt_pk_bf16_f32 v5, v8, v9
	v_lshlrev_b32_e32 v8, 16, v10
	v_and_b32_e32 v9, 0xffff0000, v10
	v_mul_f32_e32 v10, 0xbfb8aa3b, v8
	v_and_b32_e32 v17, 0xffff0000, v6
	v_mul_f32_e32 v6, 0xbfb8aa3b, v9
	v_exp_f32_e32 v10, v10
	v_exp_f32_e32 v6, v6
	v_add_f32_e32 v10, 1.0, v10
	v_add_f32_e32 v6, 1.0, v6
	v_rcp_f32_e32 v14, v10
	v_rcp_f32_e32 v15, v6
	s_nop 0
	v_pk_mul_f32 v[8:9], v[14:15], v[8:9]
	s_nop 0
	v_pk_mul_f32 v[8:9], v[8:9], v[16:17]
	v_lshlrev_b32_e32 v14, 16, v7
	v_cvt_pk_bf16_f32 v6, v8, v9
	v_lshlrev_b32_e32 v8, 16, v11
	v_and_b32_e32 v9, 0xffff0000, v11
	v_mul_f32_e32 v10, 0xbfb8aa3b, v8
	v_and_b32_e32 v15, 0xffff0000, v7
	v_mul_f32_e32 v7, 0xbfb8aa3b, v9
	v_exp_f32_e32 v10, v10
	v_exp_f32_e32 v7, v7
	v_add_f32_e32 v10, 1.0, v10
	v_add_f32_e32 v7, 1.0, v7
	v_rcp_f32_e32 v10, v10
	v_rcp_f32_e32 v11, v7
	s_nop 0
	v_pk_mul_f32 v[8:9], v[10:11], v[8:9]
	s_nop 0
	v_pk_mul_f32 v[8:9], v[8:9], v[14:15]
	s_nop 0
	v_cvt_pk_bf16_f32 v7, v8, v9
	v_add_u32_e32 v12, 128, v128
	v_mov_b32_e32 v13, 0
	v_lshlrev_b64 v[8:9], 12, v[12:13]
	v_lshl_add_u64 v[8:9], v[2:3], 0, v[8:9]
	global_store_dwordx4 v[8:9], v[4:7], off sc1
	s_nop 1
	ds_read_b128 v[4:7], v130 offset:43520
	s_waitcnt vmcnt(7)
	v_mov_b32_e32 v8, v116
	v_mov_b32_e32 v9, v117
	v_mov_b32_e32 v10, v118
	v_mov_b32_e32 v11, v119
	s_waitcnt lgkmcnt(0)
	v_lshlrev_b32_e32 v18, 16, v4
	v_and_b32_e32 v19, 0xffff0000, v4
	v_lshlrev_b32_e32 v14, 16, v8
	v_and_b32_e32 v15, 0xffff0000, v8
	v_mul_f32_e32 v8, 0xbfb8aa3b, v14
	v_mul_f32_e32 v4, 0xbfb8aa3b, v15
	v_exp_f32_e32 v8, v8
	v_exp_f32_e32 v4, v4
	v_add_f32_e32 v8, 1.0, v8
	v_add_f32_e32 v4, 1.0, v4
	v_rcp_f32_e32 v16, v8
	v_rcp_f32_e32 v17, v4
	v_lshlrev_b32_e32 v8, 16, v9
	v_and_b32_e32 v9, 0xffff0000, v9
	v_pk_mul_f32 v[14:15], v[16:17], v[14:15]
	s_nop 0
	v_pk_mul_f32 v[14:15], v[14:15], v[18:19]
	v_lshlrev_b32_e32 v16, 16, v5
	v_cvt_pk_bf16_f32 v4, v14, v15
	v_mul_f32_e32 v14, 0xbfb8aa3b, v8
	v_and_b32_e32 v17, 0xffff0000, v5
	v_mul_f32_e32 v5, 0xbfb8aa3b, v9
	v_exp_f32_e32 v14, v14
	v_exp_f32_e32 v5, v5
	v_add_f32_e32 v14, 1.0, v14
	v_add_f32_e32 v5, 1.0, v5
	v_rcp_f32_e32 v14, v14
	v_rcp_f32_e32 v15, v5
	s_nop 0
	v_pk_mul_f32 v[8:9], v[14:15], v[8:9]
	s_nop 0
	v_pk_mul_f32 v[8:9], v[8:9], v[16:17]
	v_lshlrev_b32_e32 v16, 16, v6
	v_cvt_pk_bf16_f32 v5, v8, v9
	v_lshlrev_b32_e32 v8, 16, v10
	v_and_b32_e32 v9, 0xffff0000, v10
	v_mul_f32_e32 v10, 0xbfb8aa3b, v8
	v_and_b32_e32 v17, 0xffff0000, v6
	v_mul_f32_e32 v6, 0xbfb8aa3b, v9
	v_exp_f32_e32 v10, v10
	v_exp_f32_e32 v6, v6
	v_add_f32_e32 v10, 1.0, v10
	v_add_f32_e32 v6, 1.0, v6
	v_rcp_f32_e32 v14, v10
	v_rcp_f32_e32 v15, v6
	s_nop 0
	v_pk_mul_f32 v[8:9], v[14:15], v[8:9]
	s_nop 0
	v_pk_mul_f32 v[8:9], v[8:9], v[16:17]
	v_lshlrev_b32_e32 v14, 16, v7
	v_cvt_pk_bf16_f32 v6, v8, v9
	v_lshlrev_b32_e32 v8, 16, v11
	v_and_b32_e32 v9, 0xffff0000, v11
	v_mul_f32_e32 v10, 0xbfb8aa3b, v8
	v_and_b32_e32 v15, 0xffff0000, v7
	v_mul_f32_e32 v7, 0xbfb8aa3b, v9
	v_exp_f32_e32 v10, v10
	v_exp_f32_e32 v7, v7
	v_add_f32_e32 v10, 1.0, v10
	v_add_f32_e32 v7, 1.0, v7
	v_rcp_f32_e32 v10, v10
	v_rcp_f32_e32 v11, v7
	s_nop 0
	v_pk_mul_f32 v[8:9], v[10:11], v[8:9]
	s_nop 0
	v_pk_mul_f32 v[8:9], v[8:9], v[14:15]
	s_nop 0
	v_cvt_pk_bf16_f32 v7, v8, v9
	v_add_u32_e32 v12, 160, v128
	v_mov_b32_e32 v13, 0
	v_lshlrev_b64 v[8:9], 12, v[12:13]
	v_lshl_add_u64 v[8:9], v[2:3], 0, v[8:9]
	global_store_dwordx4 v[8:9], v[4:7], off sc1
	s_nop 1
	ds_read_b128 v[4:7], v130 offset:52224
	s_waitcnt vmcnt(7)
	v_mov_b32_e32 v8, v120
	v_mov_b32_e32 v9, v121
	v_mov_b32_e32 v10, v122
	v_mov_b32_e32 v11, v123
	s_waitcnt lgkmcnt(0)
	v_lshlrev_b32_e32 v18, 16, v4
	v_and_b32_e32 v19, 0xffff0000, v4
	v_lshlrev_b32_e32 v14, 16, v8
	v_and_b32_e32 v15, 0xffff0000, v8
	v_mul_f32_e32 v8, 0xbfb8aa3b, v14
	v_mul_f32_e32 v4, 0xbfb8aa3b, v15
	v_exp_f32_e32 v8, v8
	v_exp_f32_e32 v4, v4
	v_add_f32_e32 v8, 1.0, v8
	v_add_f32_e32 v4, 1.0, v4
	v_rcp_f32_e32 v16, v8
	v_rcp_f32_e32 v17, v4
	v_lshlrev_b32_e32 v8, 16, v9
	v_and_b32_e32 v9, 0xffff0000, v9
	v_pk_mul_f32 v[14:15], v[16:17], v[14:15]
	s_nop 0
	v_pk_mul_f32 v[14:15], v[14:15], v[18:19]
	v_lshlrev_b32_e32 v16, 16, v5
	v_cvt_pk_bf16_f32 v4, v14, v15
	v_mul_f32_e32 v14, 0xbfb8aa3b, v8
	v_and_b32_e32 v17, 0xffff0000, v5
	v_mul_f32_e32 v5, 0xbfb8aa3b, v9
	v_exp_f32_e32 v14, v14
	v_exp_f32_e32 v5, v5
	v_add_f32_e32 v14, 1.0, v14
	v_add_f32_e32 v5, 1.0, v5
	v_rcp_f32_e32 v14, v14
	v_rcp_f32_e32 v15, v5
	s_nop 0
	v_pk_mul_f32 v[8:9], v[14:15], v[8:9]
	s_nop 0
	v_pk_mul_f32 v[8:9], v[8:9], v[16:17]
	v_lshlrev_b32_e32 v16, 16, v6
	v_cvt_pk_bf16_f32 v5, v8, v9
	v_lshlrev_b32_e32 v8, 16, v10
	v_and_b32_e32 v9, 0xffff0000, v10
	v_mul_f32_e32 v10, 0xbfb8aa3b, v8
	v_and_b32_e32 v17, 0xffff0000, v6
	v_mul_f32_e32 v6, 0xbfb8aa3b, v9
	v_exp_f32_e32 v10, v10
	v_exp_f32_e32 v6, v6
	v_add_f32_e32 v10, 1.0, v10
	v_add_f32_e32 v6, 1.0, v6
	v_rcp_f32_e32 v14, v10
	v_rcp_f32_e32 v15, v6
	s_nop 0
	v_pk_mul_f32 v[8:9], v[14:15], v[8:9]
	s_nop 0
	v_pk_mul_f32 v[8:9], v[8:9], v[16:17]
	v_lshlrev_b32_e32 v14, 16, v7
	v_cvt_pk_bf16_f32 v6, v8, v9
	v_lshlrev_b32_e32 v8, 16, v11
	v_and_b32_e32 v9, 0xffff0000, v11
	v_mul_f32_e32 v10, 0xbfb8aa3b, v8
	v_and_b32_e32 v15, 0xffff0000, v7
	v_mul_f32_e32 v7, 0xbfb8aa3b, v9
	v_exp_f32_e32 v10, v10
	v_exp_f32_e32 v7, v7
	v_add_f32_e32 v10, 1.0, v10
	v_add_f32_e32 v7, 1.0, v7
	v_rcp_f32_e32 v10, v10
	v_rcp_f32_e32 v11, v7
	s_nop 0
	v_pk_mul_f32 v[8:9], v[10:11], v[8:9]
	s_nop 0
	v_pk_mul_f32 v[8:9], v[8:9], v[14:15]
	s_nop 0
	v_cvt_pk_bf16_f32 v7, v8, v9
	v_add_u32_e32 v12, 192, v128
	v_mov_b32_e32 v13, 0
	v_lshlrev_b64 v[8:9], 12, v[12:13]
	v_lshl_add_u64 v[8:9], v[2:3], 0, v[8:9]
	global_store_dwordx4 v[8:9], v[4:7], off sc1
	s_nop 1
	ds_read_b128 v[4:7], v130 offset:60928
	s_waitcnt vmcnt(7)
	v_mov_b32_e32 v8, v124
	v_mov_b32_e32 v9, v125
	v_mov_b32_e32 v10, v126
	v_mov_b32_e32 v11, v127
	s_waitcnt lgkmcnt(0)
	v_lshlrev_b32_e32 v18, 16, v4
	v_and_b32_e32 v19, 0xffff0000, v4
	v_lshlrev_b32_e32 v14, 16, v8
	v_and_b32_e32 v15, 0xffff0000, v8
	v_mul_f32_e32 v8, 0xbfb8aa3b, v14
	v_mul_f32_e32 v4, 0xbfb8aa3b, v15
	v_exp_f32_e32 v8, v8
	v_exp_f32_e32 v4, v4
	v_add_f32_e32 v8, 1.0, v8
	v_add_f32_e32 v4, 1.0, v4
	v_rcp_f32_e32 v16, v8
	v_rcp_f32_e32 v17, v4
	v_lshlrev_b32_e32 v8, 16, v9
	v_and_b32_e32 v9, 0xffff0000, v9
	v_pk_mul_f32 v[14:15], v[16:17], v[14:15]
	s_nop 0
	v_pk_mul_f32 v[14:15], v[14:15], v[18:19]
	v_lshlrev_b32_e32 v16, 16, v5
	v_cvt_pk_bf16_f32 v4, v14, v15
	v_mul_f32_e32 v14, 0xbfb8aa3b, v8
	v_and_b32_e32 v17, 0xffff0000, v5
	v_mul_f32_e32 v5, 0xbfb8aa3b, v9
	v_exp_f32_e32 v14, v14
	v_exp_f32_e32 v5, v5
	v_add_f32_e32 v14, 1.0, v14
	v_add_f32_e32 v5, 1.0, v5
	v_rcp_f32_e32 v14, v14
	v_rcp_f32_e32 v15, v5
	s_nop 0
	v_pk_mul_f32 v[8:9], v[14:15], v[8:9]
	s_nop 0
	v_pk_mul_f32 v[8:9], v[8:9], v[16:17]
	v_lshlrev_b32_e32 v16, 16, v6
	v_cvt_pk_bf16_f32 v5, v8, v9
	v_lshlrev_b32_e32 v8, 16, v10
	v_and_b32_e32 v9, 0xffff0000, v10
	v_mul_f32_e32 v10, 0xbfb8aa3b, v8
	v_and_b32_e32 v17, 0xffff0000, v6
	v_mul_f32_e32 v6, 0xbfb8aa3b, v9
	v_exp_f32_e32 v10, v10
	v_exp_f32_e32 v6, v6
	v_add_f32_e32 v10, 1.0, v10
	v_add_f32_e32 v6, 1.0, v6
	v_rcp_f32_e32 v14, v10
	v_rcp_f32_e32 v15, v6
	s_nop 0
	v_pk_mul_f32 v[8:9], v[14:15], v[8:9]
	s_nop 0
	v_pk_mul_f32 v[8:9], v[8:9], v[16:17]
	v_lshlrev_b32_e32 v14, 16, v7
	v_cvt_pk_bf16_f32 v6, v8, v9
	v_lshlrev_b32_e32 v8, 16, v11
	v_and_b32_e32 v9, 0xffff0000, v11
	v_mul_f32_e32 v10, 0xbfb8aa3b, v8
	v_and_b32_e32 v15, 0xffff0000, v7
	v_mul_f32_e32 v7, 0xbfb8aa3b, v9
	v_exp_f32_e32 v10, v10
	v_exp_f32_e32 v7, v7
	v_add_f32_e32 v10, 1.0, v10
	v_add_f32_e32 v7, 1.0, v7
	v_rcp_f32_e32 v10, v10
	v_rcp_f32_e32 v11, v7
	s_nop 0
	v_pk_mul_f32 v[8:9], v[10:11], v[8:9]
	s_nop 0
	v_pk_mul_f32 v[8:9], v[8:9], v[14:15]
	s_nop 0
	v_cvt_pk_bf16_f32 v7, v8, v9
	v_add_u32_e32 v12, 224, v128
	v_mov_b32_e32 v13, 0
	v_lshlrev_b64 v[8:9], 12, v[12:13]
	v_lshl_add_u64 v[8:9], v[2:3], 0, v[8:9]
	global_store_dwordx4 v[8:9], v[4:7], off sc1
	s_nop 1
	s_movk_i32 s0, 0x1000
	s_cmpk_lg_i32 s0, 0x1000
	v_readlane_b32 s86, v246, 3
	v_readlane_b32 s92, v246, 13
	s_barrier
	s_mov_b64 s[6:7], -1
	v_readlane_b32 s87, v246, 4
	v_readlane_b32 s93, v246, 14
	v_readlane_b32 s33, v246, 17
	s_branch .LBB0_591
